# gate-prep: intra-chunk output stores widened to 16 B/lane (v_permlane16_swap), one store per direction instead of two
# baseline (speedup 1.0000x reference)
; __device__ void prep_item(const Params& p, int l, int item, LAS unsigned char* lds) {
;     ...
;         float qt[8], kh_[8], kt_[8], Tj[8];
;         cumprod32x8(E);
; #pragma unroll
;         for (int j = 0; j < 8; ++j) {
;             const float Ej = fmaxf(E[j], 1e-35f);
;             const float T0 = __builtin_bit_cast(float, __builtin_amdgcn_readlane(__builtin_bit_cast(int, Ej), 31)), T1 = __builtin_bit_cast(float, __builtin_amdgcn_readlane(__builtin_bit_cast(int, Ej), 63));
;             const float T = kh ? T1 : T0;
;             const unsigned qw = q[j >> 1]; const float qx = (j & 1) ? bf_hi(qw) : bf_lo(qw);
;             qt[j] = silu_f(qx) * 0.08838834764831845f * Ej;
;             kh_[j] = kk[j] * fast_rcp(Ej); kt_[j] = kh_[j] * T;
;             Tj[j] = T;
;         }
;         if (tau == 31) { float* dp = (float*)(p.ws + WS_DS) + ((size_t)((b * 4 + h) * 2 + dir) * NCH + ci) * 128 + k0;
;             *(f32x4*)dp = (f32x4){Tj[0], Tj[1], Tj[2], Tj[3]}; *(f32x4*)(dp + 4) = (f32x4){Tj[4], Tj[5], Tj[6], Tj[7]}; }
;         u32x4 wq, wk; wq.x = pk_bf16(qt[0], qt[1]); wq.y = pk_bf16(qt[2], qt[3]); wq.z = pk_bf16(qt[4], qt[5]); wq.w = pk_bf16(qt[6], qt[7]);
;         wk.x = pk_bf16(kh_[0], kh_[1]); wk.y = pk_bf16(kh_[2], kh_[3]); wk.z = pk_bf16(kh_[4], kh_[5]); wk.w = pk_bf16(kh_[6], kh_[7]);
;         *(LAS u32x4*)(Qs + tau * QS_ST + k0) = wq; *(LAS u32x4*)(Kh + tau * QS_ST + k0) = wk;
;         {
;           bf16_t* qd = (dir == 0) ? P + PIX(R0 + tokl, 1536 + h * 128) : (bf16_t*)(p.ws + WS_QB) + (size_t)h * PSLOT + (size_t)(R0 + tokl) * 128;
;           const int a32 = k0 & ~31, kkA = k0 & 31, kkB = kkA + 4;
;           u32x2 pa, pb; pa.x = wq.x; pa.y = wq.y; pb.x = wq.z; pb.y = wq.w;
;           *(u32x2*)(qd + a32 + 8 * ((kkA & 15) >> 2) + 4 * (kkA >> 4)) = pa;
;           *(u32x2*)(qd + a32 + 8 * ((kkB & 15) >> 2) + 4 * (kkB >> 4)) = pb; }
; #pragma unroll
;         for (int j = 0; j < 8; ++j) { Kt[(k0 + j) * KT_ST + tokl] = to_bf1(kt_[j]); const unsigned vw = v[j >> 1]; Vt[(k0 + j) * KT_ST + tau] = (bf16_t)((j & 1) ? (vw >> 16) : (vw & 0xffffu)); }
;     };
;     auto mfma_part = [&](const int dir) {
;         LAS unsigned char* db = lds + dir * P1_DIRSZ;
;         LAS bf16_t* Qs = (LAS bf16_t*)(db + P1_QS); LAS bf16_t* Kh = (LAS bf16_t*)(db + P1_KH);
;         LAS bf16_t* Vt = (LAS bf16_t*)(db + P1_VT); LAS bf16_t* Kt = (LAS bf16_t*)(db + P1_KT);
.LBB0_315:
	s_or_b64 exec, exec, s[0:1]
	v_lshlrev_b32_e32 v34, 16, v14
	v_and_b32_e32 v35, 0xffff0000, v14
	v_mul_f32_e32 v14, 0xbfb8aa3b, v34
	v_exp_f32_e32 v14, v14
	v_rcp_f32_e32 v50, v44
	v_rcp_f32_e32 v51, v45
	s_cmp_gt_u32 s73, 7
	v_add_f32_e32 v14, 1.0, v14
	v_rcp_f32_e32 v52, v14
	v_mul_f32_e32 v14, 0xbfb8aa3b, v35
	v_exp_f32_e32 v14, v14
	v_pk_mul_f32 v[22:23], v[22:23], v[50:51]
	v_readlane_b32 s6, v240, 28
	s_cselect_b64 s[0:1], -1, 0
	v_add_f32_e32 v14, 1.0, v14
	v_rcp_f32_e32 v53, v14
	v_rcp_f32_e32 v14, v42
	v_readlane_b32 s7, v240, 29
	v_mul_u32_u24_e32 v29, 0x110, v31
	v_pk_mul_f32 v[34:35], v[52:53], v[34:35]
	s_or_b64 s[6:7], s[6:7], s[0:1]
	v_pk_mul_f32 v[34:35], v[34:35], s[86:87] op_sel_hi:[1,0]
	v_readlane_b32 s0, v240, 19
	v_pk_mul_f32 v[34:35], v[34:35], v[44:45]
	v_lshlrev_b32_e32 v44, 16, v15
	v_and_b32_e32 v45, 0xffff0000, v15
	v_mul_f32_e32 v15, 0xbfb8aa3b, v44
	v_exp_f32_e32 v15, v15
	v_add3_u32 v29, s0, v29, v46
	s_mul_i32 s0, s74, 0x880000
	v_readlane_b32 s1, v242, 6
	v_add_f32_e32 v15, 1.0, v15
	v_rcp_f32_e32 v50, v15
	v_mul_f32_e32 v15, 0xbfb8aa3b, v45
	v_exp_f32_e32 v15, v15
	s_add_u32 s8, s1, s0
	v_readlane_b32 s1, v242, 7
	s_addc_u32 s9, s1, 0
	v_add_f32_e32 v15, 1.0, v15
	v_rcp_f32_e32 v51, v15
	v_rcp_f32_e32 v15, v43
	v_lshl_add_u64 v[32:33], s[8:9], 0, v[32:33]
	v_mov_b32_e32 v37, v8
	v_pk_mul_f32 v[44:45], v[50:51], v[44:45]
	v_readlane_b32 s1, v242, 60
	v_pk_mul_f32 v[44:45], v[44:45], s[86:87] op_sel_hi:[1,0]
	s_andn2_b64 vcc, exec, s[6:7]
	v_pk_mul_f32 v[44:45], v[44:45], v[42:43]
	v_pk_mul_f32 v[42:43], v[18:19], v[14:15]
	v_lshlrev_b32_e32 v18, 16, v16
	v_mul_f32_e32 v15, 0xbfb8aa3b, v18
	v_exp_f32_e32 v15, v15
	v_and_b32_e32 v19, 0xffff0000, v16
	v_rcp_f32_e32 v14, v40
	v_lshlrev_b32_e32 v16, 16, v17
	v_add_f32_e32 v15, 1.0, v15
	v_rcp_f32_e32 v50, v15
	v_mul_f32_e32 v15, 0xbfb8aa3b, v19
	v_exp_f32_e32 v15, v15
	v_and_b32_e32 v17, 0xffff0000, v17
	v_mul_f32_e32 v2, v42, v2
	v_mul_f32_e32 v3, v43, v3
	v_add_f32_e32 v15, 1.0, v15
	v_rcp_f32_e32 v51, v15
	v_rcp_f32_e32 v15, v41
	v_cvt_pk_bf16_f32 v2, v2, s0
	v_pk_mul_f32 v[18:19], v[50:51], v[18:19]
	v_pk_mul_f32 v[24:25], v[24:25], v[14:15]
	v_mul_f32_e32 v15, 0xbfb8aa3b, v16
	v_exp_f32_e32 v15, v15
	v_pk_mul_f32 v[18:19], v[18:19], s[86:87] op_sel_hi:[1,0]
	v_rcp_f32_e32 v14, v38
	v_pk_mul_f32 v[18:19], v[18:19], v[40:41]
	v_add_f32_e32 v15, 1.0, v15
	v_rcp_f32_e32 v40, v15
	v_mul_f32_e32 v15, 0xbfb8aa3b, v17
	v_exp_f32_e32 v15, v15
	v_cvt_pk_bf16_f32 v18, v18, v19
	v_mul_f32_e32 v4, v24, v4
	v_mul_f32_e32 v5, v25, v5
	v_add_f32_e32 v15, 1.0, v15
	v_rcp_f32_e32 v41, v15
	v_rcp_f32_e32 v15, v39
	v_pk_mul_f32 v[16:17], v[40:41], v[16:17]
	s_nop 0
	v_pk_mul_f32 v[16:17], v[16:17], s[86:87] op_sel_hi:[1,0]
	v_pk_mul_f32 v[20:21], v[20:21], v[14:15]
	v_pk_mul_f32 v[40:41], v[16:17], v[38:39]
	v_cvt_pk_bf16_f32 v38, v22, v23
	v_cvt_pk_bf16_f32 v19, v40, v41
	v_cvt_pk_bf16_f32 v39, v42, v43
	v_cvt_pk_bf16_f32 v40, v24, v25
	v_cvt_pk_bf16_f32 v41, v20, v21
	ds_write_b128 v29, v[38:41]
	v_mul_f32_e32 v7, v21, v7
	v_mul_f32_e32 v6, v20, v6
	v_mul_f32_e32 v20, v23, v1
	v_mul_f32_e32 v21, v22, v0
	v_lshl_add_u64 v[0:1], v[26:27], 1, v[32:33]
	v_mov_b32_e32 v29, v8
	v_lshl_add_u64 v[0:1], v[0:1], 0, v[28:29]
	v_cvt_pk_bf16_f32 v16, v34, v35
	v_cvt_pk_bf16_f32 v17, v44, v45
	v_lshl_add_u64 v[0:1], v[0:1], 0, v[36:37]
	ds_write_b128 v47, v[16:19] offset:58368
	v_lshlrev_b32_e32 v0, 1, v56
	v_lshlrev_b32_e32 v1, 1, v31
	v_cvt_pk_bf16_f32 v16, v21, s0
	v_add3_u32 v0, s1, v0, v48
	v_readlane_b32 s1, v240, 20
	ds_write_b16 v0, v16
	v_cvt_pk_bf16_f32 v16, v20, s0
	v_add3_u32 v1, s1, v1, v48
	ds_write_b16 v1, v10
	ds_write_b16 v0, v16 offset:80
	ds_write_b16_d16_hi v1, v10 offset:80
	ds_write_b16 v0, v2 offset:160
	ds_write_b16 v1, v11 offset:160
	v_cvt_pk_bf16_f32 v2, v3, s0
	ds_write_b16 v0, v2 offset:240
	ds_write_b16_d16_hi v1, v11 offset:240
	v_cvt_pk_bf16_f32 v2, v4, s0
	ds_write_b16 v0, v2 offset:320
	ds_write_b16 v1, v12 offset:320
	v_cvt_pk_bf16_f32 v2, v5, s0
	ds_write_b16 v0, v2 offset:400
	ds_write_b16_d16_hi v1, v12 offset:400
	v_cvt_pk_bf16_f32 v2, v6, s0
	v_and_b32_e32 v14, 15, v54
	v_lshrrev_b32_e32 v15, 4, v57
	ds_write_b16 v0, v2 offset:480
	ds_write_b16 v1, v13 offset:480
	v_cvt_pk_bf16_f32 v2, v7, s0
	ds_write_b16 v0, v2 offset:560
	ds_write_b16_d16_hi v1, v13 offset:560
	v_cndmask_b32_e64 v0, 0, 1, s[6:7]
	v_mul_u32_u24_e32 v1, 0x88, v14
	v_lshlrev_b32_e32 v18, 2, v15
	v_or_b32_e32 v2, v30, v14
	s_movk_i32 s1, 0x50
	v_cmp_ne_u32_e64 s[38:39], 1, v0
	v_lshlrev_b32_e32 v0, 3, v15
	v_lshlrev_b32_e32 v19, 4, v15
	v_lshlrev_b32_e32 v10, 1, v14
	v_mul_u32_u24_e32 v17, 0x140, v15
	v_and_b32_e32 v6, 48, v54
	v_mul_u32_u24_e32 v7, 0x50, v14
	v_ashrrev_i32_e32 v31, 31, v30
	v_lshlrev_b32_e32 v22, 1, v1
	v_cmp_gt_u32_e64 s[40:41], v14, v18
	v_or_b32_e32 v12, 1, v18
	v_or_b32_e32 v16, 2, v18
	v_or_b32_e32 v13, 3, v18
	v_mul_lo_u32 v11, v2, s1
	s_waitcnt lgkmcnt(0)
	s_barrier
	v_lshrrev_b32_e32 v140, 4, v135
	v_and_b32_e32 v141, 15, v135
	v_lshrrev_b32_e32 v142, 2, v141
	v_and_b32_e32 v143, 3, v141
	v_mul_u32_u24_e32 v144, 0x110, v140
	v_lshl_add_u32 v144, v142, 6, v144
	v_lshl_add_u32 v144, v143, 3, v144
	ds_read_b64 v[232:233], v144 offset:16
	ds_read_b64 v[234:235], v144 offset:48
	ds_read_b64 v[236:237], v144 offset:58384
	ds_read_b64 v[238:239], v144 offset:58416
	v_lshlrev_b32_e32 v145, 8, v140
	v_lshl_add_u32 v145, v141, 4, v145
	v_sub_u32_e32 v146, 31, v140
	v_lshlrev_b32_e32 v146, 8, v146
	v_lshl_add_u32 v146, v141, 4, v146
	s_lshr_b32 s98, s72, 7
	s_add_i32 s99, s98, 4
	s_mul_i32 s99, s99, 0x880000
	s_lshl_b32 s100, s70, 8
	s_add_u32 s99, s99, s100
	s_add_u32 s18, s82, s99
	s_addc_u32 s19, s83, 0
	s_add_i32 s98, s98, -8
	s_mul_i32 s98, s98, 0x880000
	s_add_u32 s98, s98, s100
	s_add_u32 s98, s98, 0x1b1ad000
	s_add_u32 s20, s62, s98
	s_addc_u32 s21, s63, 0
	s_waitcnt lgkmcnt(0)
	global_store_dwordx4 v145, v[232:235], s[18:19]
	global_store_dwordx4 v146, v[236:239], s[20:21]
	s_cbranch_vccnz .LBB0_317
; #define LAS __attribute__((address_space(3)))
; __device__ __forceinline__ unsigned pk_bf16(float a, float b) { f32x2 v = {a, b}; bf2_t r = __builtin_convertvector(v, bf2_t); return __builtin_bit_cast(unsigned, r); }
; __device__ __forceinline__ bf16_t to_bf1(float a) { return (bf16_t)(pk_bf16(a, 0.f) & 0xffffu); }
; __device__ void prep_item(const Params& p, int l, int item, LAS unsigned char* lds) {
;     ...
;             f32x4 a00 = (f32x4){0.f, 0.f, 0.f, 0.f}, a10 = a00, a11 = a00;
; #pragma unroll
;             for (int kb = 0; kb < 4; ++kb) {
;                 const bf16x8 qn0 = *(const LAS bf16x8*)(Qs + l15 * QS_ST + 32 * kb + 8 * q4), qn1 = *(const LAS bf16x8*)(Qs + (16 + l15) * QS_ST + 32 * kb + 8 * q4);
;                 const bf16x8 kh0 = *(const LAS bf16x8*)(Kh + l15 * QS_ST + 32 * kb + 8 * q4), kh1 = *(const LAS bf16x8*)(Kh + (16 + l15) * QS_ST + 32 * kb + 8 * q4);
;                 a00 = __builtin_amdgcn_mfma_f32_16x16x32_bf16(qn0, kh0, a00, 0, 0, 0);
;                 a10 = __builtin_amdgcn_mfma_f32_16x16x32_bf16(qn1, kh0, a10, 0, 0, 0);
;                 a11 = __builtin_amdgcn_mfma_f32_16x16x32_bf16(qn1, kh1, a11, 0, 0, 0);
;             }
; #pragma unroll
;             for (int i = 0; i < 4; ++i) { const int t = 4 * q4 + i; const bool keep = l15 <= t;
;                 Aw[t * KT_ST + l15] = to_bf1(keep ? a00[i] : 0.f);
;                 Aw[(16 + t) * KT_ST + l15] = to_bf1(a10[i]);
;                 Aw[(16 + t) * KT_ST + 16 + l15] = to_bf1(keep ? a11[i] : 0.f); }
;             asm volatile("s_waitcnt lgkmcnt(0)" ::: "memory");
;             const bf16x8 vf = *(const LAS bf16x8*)(Vt + (16 * w + l15) * KT_ST + 8 * q4);
;             bf16_t* OFB = (bf16_t*)(p.ws + WS_OFB) + (size_t)dir * NROW * 512;
; #pragma unroll
;             for (int mt = 0; mt < 2; ++mt) {
;                 const bf16x8 af = *(const LAS bf16x8*)(Aw + (16 * mt + l15) * KT_ST + 8 * q4);
;                 const f32x4 o = __builtin_amdgcn_mfma_f32_16x16x32_bf16(vf, af, (f32x4){0.f, 0.f, 0.f, 0.f}, 0, 0, 0);
;                 const int tl = 16 * mt + l15, tok = dir ? 31 - tl : tl;
;                 u32x2 wv; wv.x = pk_bf16(o[0], o[1]); wv.y = pk_bf16(o[2], o[3]);
;                 *(u32x2*)(OFB + (size_t)h * PSLOT + (size_t)(R0 + tok) * 128 + 16 * w + 4 * q4) = wv;
;             }
	v_add3_u32 v1, 16, v22, v19
	ds_read_b128 v[2:5], v1
	ds_read_b128 v[24:27], v1 offset:4352
	ds_read_b128 v[32:35], v1 offset:8704
	ds_read_b128 v[36:39], v1 offset:13056
	s_movk_i32 s1, 0x140
	v_cmp_gt_u32_e32 vcc, v14, v12
	v_add3_u32 v23, v55, v7, v6
	s_waitcnt lgkmcnt(1)
	v_mfma_f32_16x16x32_bf16 v[2:5], v[2:5], v[32:35], 0
	v_readlane_b32 s6, v242, 8
	v_readlane_b32 s7, v242, 9
	s_add_u32 s6, s6, s0
	v_mfma_f32_16x16x32_bf16 v[32:35], v[24:27], v[32:35], 0
	v_add_u32_e32 v28, s70, v14
	v_mov_b32_e32 v29, v8
	s_addc_u32 s7, s7, 0
	s_waitcnt lgkmcnt(0)
	v_mfma_f32_16x16x32_bf16 v[24:27], v[24:27], v[36:39], 0
	ds_read_b128 v[36:39], v1 offset:64
	ds_read_b128 v[40:43], v1 offset:4416
	ds_read_b128 v[44:47], v1 offset:8768
	ds_read_b128 v[48:51], v1 offset:13120
	s_waitcnt lgkmcnt(1)
	v_mfma_f32_16x16x32_bf16 v[2:5], v[36:39], v[44:47], v[2:5]
	v_mfma_f32_16x16x32_bf16 v[32:35], v[40:43], v[44:47], v[32:35]
	s_waitcnt lgkmcnt(0)
	v_mfma_f32_16x16x32_bf16 v[24:27], v[40:43], v[48:51], v[24:27]
	ds_read_b128 v[36:39], v1 offset:128
	ds_read_b128 v[40:43], v1 offset:4480
	ds_read_b128 v[44:47], v1 offset:8832
	ds_read_b128 v[48:51], v1 offset:13184
	s_waitcnt lgkmcnt(1)
	v_mfma_f32_16x16x32_bf16 v[2:5], v[36:39], v[44:47], v[2:5]
	v_mfma_f32_16x16x32_bf16 v[32:35], v[40:43], v[44:47], v[32:35]
	s_waitcnt lgkmcnt(0)
	v_mfma_f32_16x16x32_bf16 v[24:27], v[40:43], v[48:51], v[24:27]
	ds_read_b128 v[36:39], v1 offset:192
	ds_read_b128 v[40:43], v1 offset:4544
	ds_read_b128 v[44:47], v1 offset:8896
	ds_read_b128 v[48:51], v1 offset:13248
	v_add_u32_e32 v1, v55, v10
	v_mad_u32_u24 v20, v15, s1, v1
	s_waitcnt lgkmcnt(1)
	v_mfma_f32_16x16x32_bf16 v[2:5], v[36:39], v[44:47], v[2:5]
	s_movk_i32 s1, 0x50
	v_mfma_f32_16x16x32_bf16 v[32:35], v[40:43], v[44:47], v[32:35]
	s_nop 5
	v_cvt_pk_bf16_f32 v2, v2, s0
	v_cndmask_b32_e64 v2, v2, 0, s[40:41]
	ds_write_b16 v20, v2 offset:37888
	s_waitcnt lgkmcnt(1)
	v_mfma_f32_16x16x32_bf16 v[24:27], v[40:43], v[48:51], v[24:27]
	v_add3_u32 v20, v55, v17, v10
	v_cvt_pk_bf16_f32 v2, v32, s0
	ds_write_b16 v20, v2 offset:39168
	s_nop 4
	v_cvt_pk_bf16_f32 v2, v24, s0
	v_cndmask_b32_e64 v2, v2, 0, s[40:41]
	ds_write_b16 v20, v2 offset:39200
	v_cvt_pk_bf16_f32 v2, v3, s0
	v_cndmask_b32_e64 v2, v2, 0, vcc
	v_mul_u32_u24_e32 v3, 0x50, v12
	v_mad_u32_u24 v20, v12, s1, v1
	ds_write_b16 v20, v2 offset:37888
	v_cvt_pk_bf16_f32 v2, v33, s0
	v_add3_u32 v3, v55, v3, v10
	ds_write_b16 v3, v2 offset:39168
	v_cvt_pk_bf16_f32 v2, v25, s0
	v_cndmask_b32_e64 v2, v2, 0, vcc
	ds_write_b16 v3, v2 offset:39200
	v_cmp_gt_u32_e32 vcc, v14, v16
	v_cvt_pk_bf16_f32 v2, v4, s0
	v_mad_u32_u24 v3, v12, s1, s1
	v_cndmask_b32_e64 v2, v2, 0, vcc
	v_add_u32_e32 v4, v1, v3
	ds_write_b16 v4, v2 offset:37888
	v_cvt_pk_bf16_f32 v2, v34, s0
	v_add3_u32 v3, v55, v3, v10
	ds_write_b16 v3, v2 offset:39168
	v_cvt_pk_bf16_f32 v2, v26, s0
	v_cndmask_b32_e64 v2, v2, 0, vcc
	ds_write_b16 v3, v2 offset:39200
	v_cmp_gt_u32_e32 vcc, v14, v13
	v_cvt_pk_bf16_f32 v2, v5, s0
	v_mad_u32_u24 v3, v12, s1, v186
	v_cndmask_b32_e64 v2, v2, 0, vcc
	v_add_u32_e32 v1, v1, v3
	ds_write_b16 v1, v2 offset:37888
	v_cvt_pk_bf16_f32 v1, v35, s0
	v_add3_u32 v2, v55, v3, v10
	ds_write_b16 v2, v1 offset:39168
	v_cvt_pk_bf16_f32 v1, v27, s0
	v_cndmask_b32_e64 v1, v1, 0, vcc
	ds_write_b16 v2, v1 offset:39200
	s_waitcnt lgkmcnt(0)
	v_add3_u32 v1, 16, v11, v6
	ds_read_b128 v[2:5], v1 offset:17408
	ds_read_b128 v[24:27], v23 offset:37888
	s_waitcnt lgkmcnt(0)
	v_mfma_f32_16x16x32_bf16 v[24:27], v[2:5], v[24:27], 0
	v_lshlrev_b64 v[32:33], 1, v[30:31]
	v_mov_b32_e32 v1, v8
	s_nop 5
	v_cvt_pk_bf16_f32 v232, v24, v25
	v_lshlrev_b64 v[24:25], 8, v[28:29]
	v_lshl_add_u64 v[24:25], s[6:7], 0, v[24:25]
	v_lshl_add_u64 v[24:25], v[24:25], 0, v[32:33]
	v_cvt_pk_bf16_f32 v233, v26, v27
	v_lshl_add_u64 v[24:25], v[24:25], 0, v[0:1]
	v_mov_b64_e32 v[236:237], v[24:25]
	ds_read_b128 v[24:27], v23 offset:39168
	s_waitcnt lgkmcnt(0)
	v_mfma_f32_16x16x32_bf16 v[2:5], v[2:5], v[24:27], 0
	s_nop 7
	v_cvt_pk_bf16_f32 v234, v2, v3
	v_cvt_pk_bf16_f32 v235, v4, v5
	v_add_u32_e32 v4, 16, v28
	v_mov_b32_e32 v5, v8
	v_lshlrev_b64 v[4:5], 8, v[4:5]
	v_lshl_add_u64 v[4:5], s[6:7], 0, v[4:5]
	v_lshl_add_u64 v[4:5], v[4:5], 0, v[32:33]
	v_lshl_add_u64 v[4:5], v[4:5], 0, v[0:1]
	v_add_co_u32_e32 v4, vcc, -8, v4
	v_addc_co_u32_e32 v5, vcc, -1, v5, vcc
	s_mov_b32 vcc_lo, 0xffff0000
	s_mov_b32 vcc_hi, 0xffff0000
	s_nop 1
	v_cndmask_b32_e32 v236, v236, v4, vcc
	v_cndmask_b32_e32 v237, v237, v5, vcc
	v_permlane16_swap_b32_e32 v232, v234
	v_permlane16_swap_b32_e32 v233, v235
	global_store_dwordx4 v[236:237], v[232:235], off
; #define LAS __attribute__((address_space(3)))
; __device__ void prep_item(const Params& p, int l, int item, LAS unsigned char* lds) {
;     ...
;             f32x4 a00 = (f32x4){0.f, 0.f, 0.f, 0.f}, a10 = a00, a11 = a00;
; #pragma unroll
;             for (int kb = 0; kb < 4; ++kb) {
;                 const bf16x8 qn0 = *(const LAS bf16x8*)(Qs + l15 * QS_ST + 32 * kb + 8 * q4), qn1 = *(const LAS bf16x8*)(Qs + (16 + l15) * QS_ST + 32 * kb + 8 * q4);
;                 const bf16x8 kh0 = *(const LAS bf16x8*)(Kh + l15 * QS_ST + 32 * kb + 8 * q4), kh1 = *(const LAS bf16x8*)(Kh + (16 + l15) * QS_ST + 32 * kb + 8 * q4);
;                 a00 = __builtin_amdgcn_mfma_f32_16x16x32_bf16(qn0, kh0, a00, 0, 0, 0);
;                 a10 = __builtin_amdgcn_mfma_f32_16x16x32_bf16(qn1, kh0, a10, 0, 0, 0);
;                 a11 = __builtin_amdgcn_mfma_f32_16x16x32_bf16(qn1, kh1, a11, 0, 0, 0);
;             }
; #pragma unroll
;             for (int i = 0; i < 4; ++i) { const int t = 4 * q4 + i; const bool keep = l15 <= t;
;                 Aw[t * KT_ST + l15] = to_bf1(keep ? a00[i] : 0.f);
;                 Aw[(16 + t) * KT_ST + l15] = to_bf1(a10[i]);
;                 Aw[(16 + t) * KT_ST + 16 + l15] = to_bf1(keep ? a11[i] : 0.f); }
;             asm volatile("s_waitcnt lgkmcnt(0)" ::: "memory");
;             const bf16x8 vf = *(const LAS bf16x8*)(Vt + (16 * w + l15) * KT_ST + 8 * q4);
;             bf16_t* OFB = (bf16_t*)(p.ws + WS_OFB) + (size_t)dir * NROW * 512;
; #pragma unroll
;             for (int mt = 0; mt < 2; ++mt) {
;                 const bf16x8 af = *(const LAS bf16x8*)(Aw + (16 * mt + l15) * KT_ST + 8 * q4);
;                 const f32x4 o = __builtin_amdgcn_mfma_f32_16x16x32_bf16(vf, af, (f32x4){0.f, 0.f, 0.f, 0.f}, 0, 0, 0);
;                 const int tl = 16 * mt + l15, tok = dir ? 31 - tl : tl;
;                 u32x2 wv; wv.x = pk_bf16(o[0], o[1]); wv.y = pk_bf16(o[2], o[3]);
;                 *(u32x2*)(OFB + (size_t)h * PSLOT + (size_t)(R0 + tok) * 128 + 16 * w + 4 * q4) = wv;
;             }
;         }
;         { const int k = tid >> 2, part = tid & 3;
;           const u32x4 kv = *(const LAS u32x4*)(Kt + k * KT_ST + 8 * part);
;           const int pc = h * 128 + (k & 3) * 32 + (part ^ ((k >> 2) & 3)) * 8;
;           *(u32x4*)(P + PIX(R0 + (k >> 2), dir * 512 + pc)) = kv;
.LBB0_317:
	v_ashrrev_i32_e32 v1, 2, v54
	v_mul_lo_u32 v2, v1, 40
	v_lshlrev_b32_e32 v20, 1, v2
	v_lshlrev_b32_e32 v2, 3, v54
	v_and_b32_e32 v2, 24, v2
	v_lshlrev_b32_e32 v21, 1, v2
	v_ashrrev_i32_e32 v2, 4, v54
	v_add3_u32 v23, 16, v20, v21
	v_lshlrev_b32_e32 v1, 5, v1
	v_xor_b32_e32 v3, v2, v54
	ds_read_b128 v[24:27], v23 offset:27648
	v_and_b32_e32 v1, 0x60, v1
	v_lshlrev_b32_e32 v3, 3, v3
	v_add_u32_e32 v2, s70, v2
	v_and_or_b32 v1, v3, 24, v1
	v_ashrrev_i32_e32 v3, 31, v2
	s_add_u32 s6, s82, s0
	s_addc_u32 s7, s83, 0
	v_lshlrev_b64 v[2:3], 8, v[2:3]
	v_lshl_add_u64 v[28:29], s[6:7], 0, v[2:3]
	v_lshlrev_b32_e32 v4, 1, v1
	v_mov_b32_e32 v5, v8
	v_lshl_add_u64 v[28:29], v[28:29], 0, v[4:5]
	s_lshr_b32 s1, s72, 7
	s_waitcnt lgkmcnt(0)
	global_store_dwordx4 v[28:29], v[24:27], off
	ds_read_b128 v[24:27], v23 offset:17408
	s_mul_i32 s1, s1, 0x880000
	s_add_u32 s6, s82, s1
	s_addc_u32 s7, s83, 0
	v_lshl_add_u64 v[28:29], s[6:7], 0, v[2:3]
	v_lshl_add_u64 v[28:29], v[28:29], 0, v[4:5]
	s_and_b64 vcc, exec, s[38:39]
	s_waitcnt lgkmcnt(0)
	global_store_dwordx4 v[28:29], v[24:27], off
	s_cbranch_vccnz .LBB0_242
	v_add3_u32 v1, 16, v22, v19
	v_readlane_b32 s1, v240, 19
	v_cmp_gt_u32_e32 vcc, v14, v18
	v_add3_u32 v17, v9, v17, v10
	v_add3_u32 v19, s1, v22, v19
	ds_read_b128 v[22:25], v1 offset:58368
	ds_read_b128 v[26:29], v1 offset:62720
	ds_read_b128 v[32:35], v19
	ds_read_b128 v[36:39], v19 offset:4352
	s_waitcnt lgkmcnt(1)
	v_mfma_f32_16x16x32_bf16 v[22:25], v[22:25], v[32:35], 0
	s_movk_i32 s1, 0x140
	v_readlane_b32 s6, v243, 46
	v_readlane_b32 s7, v243, 47
	v_mfma_f32_16x16x32_bf16 v[32:35], v[26:29], v[32:35], 0
	s_waitcnt lgkmcnt(0)
	v_mfma_f32_16x16x32_bf16 v[26:29], v[26:29], v[36:39], 0
	ds_read_b128 v[36:39], v1 offset:58432
	ds_read_b128 v[40:43], v1 offset:62784
	ds_read_b128 v[44:47], v19 offset:64
	ds_read_b128 v[48:51], v19 offset:4416
	s_waitcnt lgkmcnt(1)
	v_mfma_f32_16x16x32_bf16 v[22:25], v[36:39], v[44:47], v[22:25]
	v_mfma_f32_16x16x32_bf16 v[32:35], v[40:43], v[44:47], v[32:35]
	s_waitcnt lgkmcnt(0)
	v_mfma_f32_16x16x32_bf16 v[26:29], v[40:43], v[48:51], v[26:29]
	ds_read_b128 v[36:39], v1 offset:58496
	ds_read_b128 v[40:43], v1 offset:62848
	ds_read_b128 v[44:47], v19 offset:128
	ds_read_b128 v[48:51], v19 offset:4480
	s_waitcnt lgkmcnt(1)
	v_mfma_f32_16x16x32_bf16 v[22:25], v[36:39], v[44:47], v[22:25]
	v_mfma_f32_16x16x32_bf16 v[32:35], v[40:43], v[44:47], v[32:35]
	s_waitcnt lgkmcnt(0)
	v_mfma_f32_16x16x32_bf16 v[26:29], v[40:43], v[48:51], v[26:29]
	ds_read_b128 v[36:39], v1 offset:58560
	ds_read_b128 v[40:43], v1 offset:62912
	ds_read_b128 v[44:47], v19 offset:192
	ds_read_b128 v[48:51], v19 offset:4544
	v_add_u32_e32 v1, v9, v10
	v_mad_u32_u24 v15, v15, s1, v1
	s_waitcnt lgkmcnt(1)
	v_mfma_f32_16x16x32_bf16 v[22:25], v[36:39], v[44:47], v[22:25]
	s_movk_i32 s1, 0x50
	v_mfma_f32_16x16x32_bf16 v[32:35], v[40:43], v[44:47], v[32:35]
	s_nop 5
	v_cvt_pk_bf16_f32 v18, v22, s0
	v_cndmask_b32_e64 v18, v18, 0, vcc
	ds_write_b16 v15, v18
	s_waitcnt lgkmcnt(1)
	v_mfma_f32_16x16x32_bf16 v[26:29], v[40:43], v[48:51], v[26:29]
	v_mad_u32_u24 v18, v12, s1, v1
	v_cvt_pk_bf16_f32 v15, v32, s0
	ds_write_b16 v17, v15 offset:1280
	s_nop 4
	v_cvt_pk_bf16_f32 v15, v26, s0
	v_cndmask_b32_e64 v15, v15, 0, vcc
	ds_write_b16 v17, v15 offset:1312
	v_cmp_gt_u32_e32 vcc, v14, v12
	v_cvt_pk_bf16_f32 v15, v23, s0
	v_mul_u32_u24_e32 v17, 0x50, v12
	v_cndmask_b32_e64 v15, v15, 0, vcc
	ds_write_b16 v18, v15
	v_cvt_pk_bf16_f32 v15, v33, s0
	v_add3_u32 v17, v9, v17, v10
	ds_write_b16 v17, v15 offset:1280
	v_cvt_pk_bf16_f32 v15, v27, s0
	v_cndmask_b32_e64 v15, v15, 0, vcc
	ds_write_b16 v17, v15 offset:1312
	v_cmp_gt_u32_e32 vcc, v14, v16
	v_cvt_pk_bf16_f32 v15, v24, s0
	v_mad_u32_u24 v16, v12, s1, s1
	v_cndmask_b32_e64 v15, v15, 0, vcc
	v_add_u32_e32 v17, v1, v16
	ds_write_b16 v17, v15
	v_cvt_pk_bf16_f32 v15, v34, s0
	v_add3_u32 v16, v9, v16, v10
	ds_write_b16 v16, v15 offset:1280
	v_cvt_pk_bf16_f32 v15, v28, s0
	v_cndmask_b32_e64 v15, v15, 0, vcc
	v_cmp_gt_u32_e32 vcc, v14, v13
	v_cvt_pk_bf16_f32 v13, v25, s0
	v_mad_u32_u24 v12, v12, s1, v186
	v_cndmask_b32_e64 v13, v13, 0, vcc
	v_add_u32_e32 v1, v1, v12
	ds_write_b16 v1, v13
	v_cvt_pk_bf16_f32 v1, v35, s0
	v_add3_u32 v10, v9, v12, v10
	ds_write_b16 v10, v1 offset:1280
	v_cvt_pk_bf16_f32 v1, v29, s0
	v_cndmask_b32_e64 v1, v1, 0, vcc
	ds_write_b16 v16, v15 offset:1312
	ds_write_b16 v10, v1 offset:1312
	v_readlane_b32 s1, v240, 20
	s_waitcnt lgkmcnt(0)
	v_add3_u32 v9, v9, v7, v6
	ds_read_b128 v[16:19], v9
	v_add3_u32 v1, s1, v11, v6
	ds_read_b128 v[10:13], v1
	s_waitcnt lgkmcnt(0)
	v_mfma_f32_16x16x32_bf16 v[16:19], v[10:13], v[16:19], 0
	s_add_u32 s0, s6, s0
	s_addc_u32 s1, s7, 0
	v_lshlrev_b64 v[22:23], 1, v[30:31]
	s_nop 4
	v_cvt_pk_bf16_f32 v232, v16, v17
	v_xad_u32 v16, v14, 31, s70
	v_mov_b32_e32 v17, v8
	v_lshlrev_b64 v[16:17], 8, v[16:17]
	v_lshl_add_u64 v[16:17], s[0:1], 0, v[16:17]
	v_lshl_add_u64 v[16:17], v[16:17], 0, v[22:23]
	v_mov_b32_e32 v1, v8
	v_cvt_pk_bf16_f32 v233, v18, v19
	v_lshl_add_u64 v[16:17], v[16:17], 0, v[0:1]
	v_mov_b64_e32 v[236:237], v[16:17]
	ds_read_b128 v[16:19], v9 offset:1280
	s_waitcnt lgkmcnt(0)
	v_mfma_f32_16x16x32_bf16 v[10:13], v[10:13], v[16:19], 0
	s_nop 7
	v_cvt_pk_bf16_f32 v234, v10, v11
	v_xad_u32 v10, v14, 15, s70
	v_mov_b32_e32 v11, v8
	v_lshlrev_b64 v[10:11], 8, v[10:11]
	v_lshl_add_u64 v[10:11], s[0:1], 0, v[10:11]
	v_lshl_add_u64 v[10:11], v[10:11], 0, v[22:23]
	v_cvt_pk_bf16_f32 v235, v12, v13
	v_lshl_add_u64 v[0:1], v[10:11], 0, v[0:1]
	v_add_co_u32_e32 v0, vcc, -8, v0
	v_addc_co_u32_e32 v1, vcc, -1, v1, vcc
	s_mov_b32 vcc_lo, 0xffff0000
	s_mov_b32 vcc_hi, 0xffff0000
	s_nop 1
	v_cndmask_b32_e32 v236, v236, v0, vcc
	v_cndmask_b32_e32 v237, v237, v1, vcc
	v_permlane16_swap_b32_e32 v232, v234
	v_permlane16_swap_b32_e32 v233, v235
	global_store_dwordx4 v[236:237], v[232:235], off
	s_branch .LBB0_242
